# P0 row conversion loop rewritten: 16 loads of a row in flight with constant vmcnt(15) steps instead of hipcc's 16 serialised load-wait-store rounds
# speedup vs baseline: 1.0016x; 1.0016x over previous
; __device__ __forceinline__ unsigned cvt_pk_bf16(float lo, float hi) { const f32x2c_t v = {lo, hi}; return __builtin_bit_cast(unsigned, __builtin_convertvector(v, bf16x2c_t)); }
; __device__ __forceinline__ void cvt_rows_bf16(const float* x, bf16* out, float* part, int gw, int ngw, int lane) {
;     for (int m = gw; m < M; m += ngw) {
;         const f32x4* xr = (const f32x4*)(x + (size_t)m * DM) + lane;
;         v2u* o = (v2u*)(out + (size_t)m * DM) + lane;
;         float ss = 0.f;
; #pragma unroll
;         for (int j = 0; j < 16; ++j) { const f32x4 v = xr[64 * j]; ss += (v[0] * v[0] + v[1] * v[1]) + (v[2] * v[2] + v[3] * v[3]);
;             v2u ov; ov[0] = cvt_pk_bf16(v[0], v[1]); ov[1] = cvt_pk_bf16(v[2], v[3]); o[64 * j] = ov; }
;         ss = wave_sum(ss);
;         part[(size_t)m * 64 + lane] = (lane == 0) ? ss : 0.f;
;     }
; }
.LBB0_35:
	v_add_co_u32_e32 v10, vcc, s1, v18
	s_nop 1
	v_addc_co_u32_e32 v11, vcc, 0, v19, vcc
	v_add_co_u32_e32 v12, vcc, s2, v18
	s_nop 1
	v_addc_co_u32_e32 v13, vcc, 0, v19, vcc
	v_add_co_u32_e32 v194, vcc, s9, v18
	s_nop 1
	v_addc_co_u32_e32 v195, vcc, 0, v19, vcc
	global_load_dwordx4 v[32:35], v[18:19], off
	global_load_dwordx4 v[36:39], v[18:19], off offset:1024
	global_load_dwordx4 v[40:43], v[18:19], off offset:2048
	global_load_dwordx4 v[44:47], v[18:19], off offset:3072
	global_load_dwordx4 v[48:51], v[10:11], off
	global_load_dwordx4 v[52:55], v[10:11], off offset:1024
	global_load_dwordx4 v[56:59], v[10:11], off offset:2048
	global_load_dwordx4 v[60:63], v[10:11], off offset:3072
	global_load_dwordx4 v[64:67], v[12:13], off
	global_load_dwordx4 v[68:71], v[12:13], off offset:1024
	global_load_dwordx4 v[72:75], v[12:13], off offset:2048
	global_load_dwordx4 v[76:79], v[12:13], off offset:3072
	global_load_dwordx4 v[178:181], v[194:195], off
	global_load_dwordx4 v[182:185], v[194:195], off offset:1024
	global_load_dwordx4 v[186:189], v[194:195], off offset:2048
	global_load_dwordx4 v[190:193], v[194:195], off offset:3072
	v_lshl_add_u64 v[8:9], s[46:47], 0, v[20:21]
	v_add_co_u32_e32 v14, vcc, s0, v8
	s_nop 1
	v_addc_co_u32_e32 v15, vcc, 0, v9, vcc
	v_add_co_u32_e32 v22, vcc, s3, v8
	s_nop 1
	v_addc_co_u32_e32 v23, vcc, 0, v9, vcc
	v_lshl_add_u64 v[196:197], s[46:47], 0, v[16:17]
	v_lshl_add_u64 v[18:19], v[18:19], 0, s[12:13]
	v_lshl_add_u64 v[20:21], v[20:21], 0, s[14:15]
	v_lshl_add_u64 v[16:17], v[16:17], 0, s[10:11]
	s_waitcnt vmcnt(15)
	v_cvt_pk_bf16_f32 v6, v32, v33
	v_cvt_pk_bf16_f32 v7, v34, v35
	global_store_dwordx2 v[14:15], v[6:7], off
	v_pk_mul_f32 v[2:3], v[32:33], v[32:33]
	v_pk_mul_f32 v[4:5], v[34:35], v[34:35]
	v_add_f32_e32 v2, v2, v3
	v_add_f32_e32 v4, v4, v5
	v_add_f32_e32 v0, v2, v4
	s_waitcnt vmcnt(15)
	v_cvt_pk_bf16_f32 v198, v36, v37
	v_cvt_pk_bf16_f32 v199, v38, v39
	global_store_dwordx2 v[14:15], v[198:199], off offset:512
	v_pk_mul_f32 v[2:3], v[36:37], v[36:37]
	v_pk_mul_f32 v[4:5], v[38:39], v[38:39]
	v_add_f32_e32 v2, v2, v3
	v_add_f32_e32 v4, v4, v5
	v_add_f32_e32 v2, v2, v4
	v_add_f32_e32 v0, v0, v2
	s_waitcnt vmcnt(15)
	v_cvt_pk_bf16_f32 v6, v40, v41
	v_cvt_pk_bf16_f32 v7, v42, v43
	global_store_dwordx2 v[14:15], v[6:7], off offset:1024
	v_pk_mul_f32 v[2:3], v[40:41], v[40:41]
	v_pk_mul_f32 v[4:5], v[42:43], v[42:43]
	v_add_f32_e32 v2, v2, v3
	v_add_f32_e32 v4, v4, v5
	v_add_f32_e32 v2, v2, v4
	v_add_f32_e32 v0, v0, v2
	s_waitcnt vmcnt(15)
	v_cvt_pk_bf16_f32 v198, v44, v45
	v_cvt_pk_bf16_f32 v199, v46, v47
	global_store_dwordx2 v[14:15], v[198:199], off offset:1536
	v_pk_mul_f32 v[2:3], v[44:45], v[44:45]
	v_pk_mul_f32 v[4:5], v[46:47], v[46:47]
	v_add_f32_e32 v2, v2, v3
	v_add_f32_e32 v4, v4, v5
	v_add_f32_e32 v2, v2, v4
	v_add_f32_e32 v0, v0, v2
	s_waitcnt vmcnt(15)
	v_cvt_pk_bf16_f32 v6, v48, v49
	v_cvt_pk_bf16_f32 v7, v50, v51
	global_store_dwordx2 v[14:15], v[6:7], off offset:2048
	v_pk_mul_f32 v[2:3], v[48:49], v[48:49]
	v_pk_mul_f32 v[4:5], v[50:51], v[50:51]
	v_add_f32_e32 v2, v2, v3
	v_add_f32_e32 v4, v4, v5
	v_add_f32_e32 v2, v2, v4
	v_add_f32_e32 v0, v0, v2
	s_waitcnt vmcnt(15)
	v_cvt_pk_bf16_f32 v198, v52, v53
	v_cvt_pk_bf16_f32 v199, v54, v55
	global_store_dwordx2 v[14:15], v[198:199], off offset:2560
	v_pk_mul_f32 v[2:3], v[52:53], v[52:53]
	v_pk_mul_f32 v[4:5], v[54:55], v[54:55]
	v_add_f32_e32 v2, v2, v3
	v_add_f32_e32 v4, v4, v5
	v_add_f32_e32 v2, v2, v4
	v_add_f32_e32 v0, v0, v2
	s_waitcnt vmcnt(15)
	v_cvt_pk_bf16_f32 v6, v56, v57
	v_cvt_pk_bf16_f32 v7, v58, v59
	global_store_dwordx2 v[14:15], v[6:7], off offset:3072
	v_pk_mul_f32 v[2:3], v[56:57], v[56:57]
	v_pk_mul_f32 v[4:5], v[58:59], v[58:59]
	v_add_f32_e32 v2, v2, v3
	v_add_f32_e32 v4, v4, v5
	v_add_f32_e32 v2, v2, v4
	v_add_f32_e32 v0, v0, v2
	s_waitcnt vmcnt(15)
; __device__ __forceinline__ unsigned cvt_pk_bf16(float lo, float hi) { const f32x2c_t v = {lo, hi}; return __builtin_bit_cast(unsigned, __builtin_convertvector(v, bf16x2c_t)); }
; __device__ __forceinline__ float wave_sum(float v) {
; #pragma unroll
;     for (int o = 1; o < 64; o <<= 1) v += __shfl_xor(v, o);
;     return v;
; }
; __device__ __forceinline__ void cvt_rows_bf16(const float* x, bf16* out, float* part, int gw, int ngw, int lane) {
;     ...
;         for (int j = 0; j < 16; ++j) { const f32x4 v = xr[64 * j]; ss += (v[0] * v[0] + v[1] * v[1]) + (v[2] * v[2] + v[3] * v[3]);
;             v2u ov; ov[0] = cvt_pk_bf16(v[0], v[1]); ov[1] = cvt_pk_bf16(v[2], v[3]); o[64 * j] = ov; }
;         ss = wave_sum(ss);
;         part[(size_t)m * 64 + lane] = (lane == 0) ? ss : 0.f;
;     }
	v_cvt_pk_bf16_f32 v198, v60, v61
	v_cvt_pk_bf16_f32 v199, v62, v63
	global_store_dwordx2 v[14:15], v[198:199], off offset:3584
	v_pk_mul_f32 v[2:3], v[60:61], v[60:61]
	v_pk_mul_f32 v[4:5], v[62:63], v[62:63]
	v_add_f32_e32 v2, v2, v3
	v_add_f32_e32 v4, v4, v5
	v_add_f32_e32 v2, v2, v4
	v_add_f32_e32 v0, v0, v2
	s_waitcnt vmcnt(15)
	v_cvt_pk_bf16_f32 v6, v64, v65
	v_cvt_pk_bf16_f32 v7, v66, v67
	global_store_dwordx2 v[22:23], v[6:7], off
	v_pk_mul_f32 v[2:3], v[64:65], v[64:65]
	v_pk_mul_f32 v[4:5], v[66:67], v[66:67]
	v_add_f32_e32 v2, v2, v3
	v_add_f32_e32 v4, v4, v5
	v_add_f32_e32 v2, v2, v4
	v_add_f32_e32 v0, v0, v2
	s_waitcnt vmcnt(15)
	v_cvt_pk_bf16_f32 v198, v68, v69
	v_cvt_pk_bf16_f32 v199, v70, v71
	global_store_dwordx2 v[22:23], v[198:199], off offset:512
	v_pk_mul_f32 v[2:3], v[68:69], v[68:69]
	v_pk_mul_f32 v[4:5], v[70:71], v[70:71]
	v_add_f32_e32 v2, v2, v3
	v_add_f32_e32 v4, v4, v5
	v_add_f32_e32 v2, v2, v4
	v_add_f32_e32 v0, v0, v2
	s_waitcnt vmcnt(15)
	v_cvt_pk_bf16_f32 v6, v72, v73
	v_cvt_pk_bf16_f32 v7, v74, v75
	global_store_dwordx2 v[22:23], v[6:7], off offset:1024
	v_pk_mul_f32 v[2:3], v[72:73], v[72:73]
	v_pk_mul_f32 v[4:5], v[74:75], v[74:75]
	v_add_f32_e32 v2, v2, v3
	v_add_f32_e32 v4, v4, v5
	v_add_f32_e32 v2, v2, v4
	v_add_f32_e32 v0, v0, v2
	s_waitcnt vmcnt(15)
	v_cvt_pk_bf16_f32 v198, v76, v77
	v_cvt_pk_bf16_f32 v199, v78, v79
	global_store_dwordx2 v[22:23], v[198:199], off offset:1536
	v_pk_mul_f32 v[2:3], v[76:77], v[76:77]
	v_pk_mul_f32 v[4:5], v[78:79], v[78:79]
	v_add_f32_e32 v2, v2, v3
	v_add_f32_e32 v4, v4, v5
	v_add_f32_e32 v2, v2, v4
	v_add_f32_e32 v0, v0, v2
	s_waitcnt vmcnt(15)
	v_cvt_pk_bf16_f32 v6, v178, v179
	v_cvt_pk_bf16_f32 v7, v180, v181
	global_store_dwordx2 v[22:23], v[6:7], off offset:2048
	v_pk_mul_f32 v[2:3], v[178:179], v[178:179]
	v_pk_mul_f32 v[4:5], v[180:181], v[180:181]
	v_add_f32_e32 v2, v2, v3
	v_add_f32_e32 v4, v4, v5
	v_add_f32_e32 v2, v2, v4
	v_add_f32_e32 v0, v0, v2
	s_waitcnt vmcnt(15)
	v_cvt_pk_bf16_f32 v198, v182, v183
	v_cvt_pk_bf16_f32 v199, v184, v185
	global_store_dwordx2 v[22:23], v[198:199], off offset:2560
	v_pk_mul_f32 v[2:3], v[182:183], v[182:183]
	v_pk_mul_f32 v[4:5], v[184:185], v[184:185]
	v_add_f32_e32 v2, v2, v3
	v_add_f32_e32 v4, v4, v5
	v_add_f32_e32 v2, v2, v4
	v_add_f32_e32 v0, v0, v2
	s_waitcnt vmcnt(15)
	v_cvt_pk_bf16_f32 v6, v186, v187
	v_cvt_pk_bf16_f32 v7, v188, v189
	global_store_dwordx2 v[22:23], v[6:7], off offset:3072
	v_pk_mul_f32 v[2:3], v[186:187], v[186:187]
	v_pk_mul_f32 v[4:5], v[188:189], v[188:189]
	v_add_f32_e32 v2, v2, v3
	v_add_f32_e32 v4, v4, v5
	v_add_f32_e32 v2, v2, v4
	v_add_f32_e32 v0, v0, v2
	s_waitcnt vmcnt(15)
	v_cvt_pk_bf16_f32 v198, v190, v191
	v_cvt_pk_bf16_f32 v199, v192, v193
	global_store_dwordx2 v[22:23], v[198:199], off offset:3584
	v_pk_mul_f32 v[2:3], v[190:191], v[190:191]
	v_pk_mul_f32 v[4:5], v[192:193], v[192:193]
	v_add_f32_e32 v2, v2, v3
	v_add_f32_e32 v4, v4, v5
	v_add_f32_e32 v2, v2, v4
	v_add_f32_e32 v0, v0, v2
	ds_bpermute_b32 v1, v25, v0
	s_waitcnt lgkmcnt(0)
	v_add_f32_e32 v0, v0, v1
	ds_bpermute_b32 v1, v26, v0
	s_waitcnt lgkmcnt(0)
	v_add_f32_e32 v0, v0, v1
	ds_bpermute_b32 v1, v27, v0
	s_waitcnt lgkmcnt(0)
	v_add_f32_e32 v0, v0, v1
	ds_bpermute_b32 v1, v28, v0
	s_waitcnt lgkmcnt(0)
	v_add_f32_e32 v0, v0, v1
	ds_bpermute_b32 v1, v29, v0
	s_waitcnt lgkmcnt(0)
	v_add_f32_e32 v0, v0, v1
	ds_bpermute_b32 v1, v30, v0
	s_waitcnt lgkmcnt(0)
	v_add_f32_e32 v0, v0, v1
	v_cndmask_b32_e64 v0, 0, v0, s[4:5]
	global_store_dword v[196:197], v0, off
	s_add_i32 s8, s8, s68
	s_cmpk_lt_i32 s8, 0x4000
	s_cbranch_scc1 .LBB0_35
